# bar
# baseline (speedup 1.0000x reference)
; __device__ __forceinline__ unsigned xb_ld(unsigned* p) { return __hip_atomic_load(p, __ATOMIC_RELAXED, __HIP_MEMORY_SCOPE_AGENT); }
; __device__ __forceinline__ unsigned xb_add(unsigned* p, unsigned v) { return __hip_atomic_fetch_add(p, v, __ATOMIC_RELAXED, __HIP_MEMORY_SCOPE_AGENT); }
; #define XB_SPIN(cond, bar) do { unsigned _sp = 0; while (cond) { __builtin_amdgcn_s_sleep(1); \
;     if ((++_sp & 255u) == 0u) { if (xb_ld(&(bar)[XB_TMO])) break; if (_sp > XB_SPIN_CAP) { atomicAdd(&(bar)[XB_TMO], 1u); break; } } } } while (0)
; __device__ __forceinline__ void xcd_barrier(const XcdBarrier& b) {
;     ...
;   if (threadIdx.x == 0) {
;     unsigned* bar = b.bar;
;     __builtin_amdgcn_s_waitcnt(0);
;     const unsigned old = xb_add(&bar[XB_XSUB(b.x)], 1u);
;     const unsigned gen = old / b.nloc;
;     if (old + 1u == (gen + 1u) * b.nloc) {
;       __builtin_amdgcn_fence(__ATOMIC_RELEASE, "agent");
;       asm volatile("s_waitcnt vmcnt(0)" ::: "memory");
;       const unsigned og = xb_add(&bar[XB_TOP], 1u);
;       const unsigned tg = og / b.nx;
;       if (og + 1u == (tg + 1u) * b.nx) xb_add(&bar[XB_TOPGEN], 1u);
;       else XB_SPIN(xb_ld(&bar[XB_TOPGEN]) == tg, bar);
;       __builtin_amdgcn_fence(__ATOMIC_ACQUIRE, "agent");
;       xb_add(&bar[XB_XGEN(b.x)], 1u);
;     } else {
;       XB_SPIN(xb_ld(&bar[XB_XGEN(b.x)]) == gen, bar);
;       __builtin_amdgcn_fence(__ATOMIC_ACQUIRE, "agent");
;     }
.LBB0_173:
	v_cvt_f32_u32_e32 v0, s90
	s_waitcnt vmcnt(0)
	s_barrier
	v_rcp_iflag_f32_e32 v207, v0
	s_and_saveexec_b64 s[4:5], s[0:1]
	s_cbranch_execz .LBB0_206
	v_add_co_u32_e32 v0, vcc, 0x1000, v192
	v_mov_b32_e32 v2, 1
	s_nop 0
	v_addc_co_u32_e32 v1, vcc, 0, v193, vcc
	s_waitcnt vmcnt(0) expcnt(0) lgkmcnt(0)
	global_atomic_add v0, v[0:1], v2, off offset:1024 sc0
	v_mul_f32_e32 v1, 0x4f7ffffe, v207
	v_cvt_u32_f32_e32 v1, v1
	s_sub_i32 s6, 0, s90
	v_mul_lo_u32 v2, s6, v1
	v_mul_hi_u32 v2, v1, v2
	v_add_u32_e32 v1, v1, v2
	s_waitcnt vmcnt(0)
	v_mul_hi_u32 v1, v0, v1
	v_mul_lo_u32 v2, v1, s90
	v_sub_u32_e32 v2, v0, v2
	v_add_u32_e32 v3, 1, v1
	v_cmp_le_u32_e32 vcc, s90, v2
	v_add_u32_e32 v0, 1, v0
	s_nop 0
	v_cndmask_b32_e32 v1, v1, v3, vcc
	v_subrev_u32_e32 v3, s90, v2
	v_cndmask_b32_e32 v2, v2, v3, vcc
	v_add_u32_e32 v3, 1, v1
	v_cmp_le_u32_e32 vcc, s90, v2
	s_nop 1
	v_cndmask_b32_e32 v2, v1, v3, vcc
	v_mul_lo_u32 v1, s90, v2
	v_add_u32_e32 v1, s90, v1
	v_cmp_ne_u32_e32 vcc, v0, v1
	s_and_saveexec_b64 s[6:7], vcc
	s_xor_b64 s[6:7], exec, s[6:7]
	s_cbranch_execz .LBB0_188
	v_mov_b32_e32 v0, 0xe7a3500
	v_mov_b32_e32 v1, s61
	v_add_co_u32_e32 v0, vcc, s60, v0
	s_nop 1
	v_addc_co_u32_e32 v1, vcc, 0, v1, vcc
	global_load_dword v0, v[0:1], off sc1
	s_waitcnt vmcnt(0)
	v_cmp_eq_u32_e32 vcc, v0, v2
	s_and_saveexec_b64 s[8:9], vcc
	s_cbranch_execz .LBB0_187
	s_add_u32 s10, s60, 0xe7a3500
	s_addc_u32 s11, s61, 0
	v_mov_b32_e32 v0, s10
	v_mov_b32_e32 v1, s11
	s_nop 0
	s_add_u32 s10, s60, 0xe7a0200
	s_addc_u32 s11, s61, 0
	s_mov_b32 s19, 1
	s_mov_b64 s[20:21], 0
	v_mov_b32_e32 v3, 0
	s_branch .LBB0_178

; __device__ __forceinline__ unsigned xb_ld(unsigned* p) { return __hip_atomic_load(p, __ATOMIC_RELAXED, __HIP_MEMORY_SCOPE_AGENT); }
; __device__ __forceinline__ unsigned xb_add(unsigned* p, unsigned v) { return __hip_atomic_fetch_add(p, v, __ATOMIC_RELAXED, __HIP_MEMORY_SCOPE_AGENT); }
; #define XB_SPIN(cond, bar) do { unsigned _sp = 0; while (cond) { __builtin_amdgcn_s_sleep(1); \
;     if ((++_sp & 255u) == 0u) { if (xb_ld(&(bar)[XB_TMO])) break; if (_sp > XB_SPIN_CAP) { atomicAdd(&(bar)[XB_TMO], 1u); break; } } } } while (0)
; __device__ __forceinline__ void xcd_barrier(const XcdBarrier& b) {
;     ...
;   if (threadIdx.x == 0) {
;     unsigned* bar = b.bar;
;     __builtin_amdgcn_s_waitcnt(0);
;     const unsigned old = xb_add(&bar[XB_XSUB(b.x)], 1u);
;     const unsigned gen = old / b.nloc;
;     if (old + 1u == (gen + 1u) * b.nloc) {
;       __builtin_amdgcn_fence(__ATOMIC_RELEASE, "agent");
;       asm volatile("s_waitcnt vmcnt(0)" ::: "memory");
;       const unsigned og = xb_add(&bar[XB_TOP], 1u);
;       const unsigned tg = og / b.nx;
;       if (og + 1u == (tg + 1u) * b.nx) xb_add(&bar[XB_TOPGEN], 1u);
;       else XB_SPIN(xb_ld(&bar[XB_TOPGEN]) == tg, bar);
;       __builtin_amdgcn_fence(__ATOMIC_ACQUIRE, "agent");
;       xb_add(&bar[XB_XGEN(b.x)], 1u);
;     } else {
;       XB_SPIN(xb_ld(&bar[XB_XGEN(b.x)]) == gen, bar);
;       __builtin_amdgcn_fence(__ATOMIC_ACQUIRE, "agent");
;     }
.LBB0_278:
	s_waitcnt vmcnt(0)
	s_barrier
	s_and_saveexec_b64 s[4:5], s[0:1]
	s_cbranch_execz .LBB0_311
	v_add_co_u32_e32 v0, vcc, 0x1000, v192
	v_mov_b32_e32 v2, 1
	s_nop 0
	v_addc_co_u32_e32 v1, vcc, 0, v193, vcc
	s_waitcnt vmcnt(0) expcnt(0) lgkmcnt(0)
	global_atomic_add v0, v[0:1], v2, off offset:1024 sc0
	v_mul_f32_e32 v1, 0x4f7ffffe, v207
	v_cvt_u32_f32_e32 v1, v1
	s_sub_i32 s3, 0, s90
	v_mul_lo_u32 v2, s3, v1
	v_mul_hi_u32 v2, v1, v2
	v_add_u32_e32 v1, v1, v2
	s_waitcnt vmcnt(0)
	v_mul_hi_u32 v1, v0, v1
	v_mul_lo_u32 v2, v1, s90
	v_sub_u32_e32 v2, v0, v2
	v_add_u32_e32 v3, 1, v1
	v_cmp_le_u32_e32 vcc, s90, v2
	v_add_u32_e32 v0, 1, v0
	s_nop 0
	v_cndmask_b32_e32 v1, v1, v3, vcc
	v_subrev_u32_e32 v3, s90, v2
	v_cndmask_b32_e32 v2, v2, v3, vcc
	v_add_u32_e32 v3, 1, v1
	v_cmp_le_u32_e32 vcc, s90, v2
	s_nop 1
	v_cndmask_b32_e32 v2, v1, v3, vcc
	v_mul_lo_u32 v1, s90, v2
	v_add_u32_e32 v1, s90, v1
	v_cmp_ne_u32_e32 vcc, v0, v1
	s_and_saveexec_b64 s[6:7], vcc
	s_xor_b64 s[6:7], exec, s[6:7]
	s_cbranch_execz .LBB0_293
	v_mov_b32_e32 v0, 0xe7a3500
	v_mov_b32_e32 v1, s61
	v_add_co_u32_e32 v0, vcc, s60, v0
	s_nop 1
	v_addc_co_u32_e32 v1, vcc, 0, v1, vcc
	global_load_dword v0, v[0:1], off sc1
	s_waitcnt vmcnt(0)
	v_cmp_eq_u32_e32 vcc, v0, v2
	s_and_saveexec_b64 s[8:9], vcc
	s_cbranch_execz .LBB0_292
	s_add_u32 s10, s60, 0xe7a3500
	s_addc_u32 s11, s61, 0
	v_mov_b32_e32 v0, s10
	v_mov_b32_e32 v1, s11
	s_nop 0
	s_add_u32 s10, s60, 0xe7a0200
	s_addc_u32 s11, s61, 0
	s_mov_b32 s3, 1
	s_mov_b64 s[24:25], 0
	v_mov_b32_e32 v3, 0
	s_branch .LBB0_283

; __device__ __forceinline__ unsigned xb_ld(unsigned* p) { return __hip_atomic_load(p, __ATOMIC_RELAXED, __HIP_MEMORY_SCOPE_AGENT); }
; __device__ __forceinline__ unsigned xb_add(unsigned* p, unsigned v) { return __hip_atomic_fetch_add(p, v, __ATOMIC_RELAXED, __HIP_MEMORY_SCOPE_AGENT); }
; #define XB_SPIN(cond, bar) do { unsigned _sp = 0; while (cond) { __builtin_amdgcn_s_sleep(1); \
;     if ((++_sp & 255u) == 0u) { if (xb_ld(&(bar)[XB_TMO])) break; if (_sp > XB_SPIN_CAP) { atomicAdd(&(bar)[XB_TMO], 1u); break; } } } } while (0)
; __device__ __forceinline__ void xcd_barrier(const XcdBarrier& b) {
;     ...
;   if (threadIdx.x == 0) {
;     unsigned* bar = b.bar;
;     __builtin_amdgcn_s_waitcnt(0);
;     const unsigned old = xb_add(&bar[XB_XSUB(b.x)], 1u);
;     const unsigned gen = old / b.nloc;
;     if (old + 1u == (gen + 1u) * b.nloc) {
;       __builtin_amdgcn_fence(__ATOMIC_RELEASE, "agent");
;       asm volatile("s_waitcnt vmcnt(0)" ::: "memory");
;       const unsigned og = xb_add(&bar[XB_TOP], 1u);
;       const unsigned tg = og / b.nx;
;       if (og + 1u == (tg + 1u) * b.nx) xb_add(&bar[XB_TOPGEN], 1u);
;       else XB_SPIN(xb_ld(&bar[XB_TOPGEN]) == tg, bar);
;       __builtin_amdgcn_fence(__ATOMIC_ACQUIRE, "agent");
;       xb_add(&bar[XB_XGEN(b.x)], 1u);
;     } else {
;       XB_SPIN(xb_ld(&bar[XB_XGEN(b.x)]) == gen, bar);
;       __builtin_amdgcn_fence(__ATOMIC_ACQUIRE, "agent");
;     }
.LBB0_463:
	s_waitcnt vmcnt(0)
	s_barrier
	s_and_saveexec_b64 s[4:5], s[0:1]
	s_cbranch_execz .LBB0_496
	v_add_co_u32_e32 v0, vcc, 0x1000, v192
	v_mov_b32_e32 v2, 1
	s_nop 0
	v_addc_co_u32_e32 v1, vcc, 0, v193, vcc
	s_waitcnt vmcnt(0) expcnt(0) lgkmcnt(0)
	global_atomic_add v0, v[0:1], v2, off offset:1024 sc0
	v_mul_f32_e32 v1, 0x4f7ffffe, v207
	v_cvt_u32_f32_e32 v1, v1
	s_sub_i32 s3, 0, s90
	v_mul_lo_u32 v2, s3, v1
	v_mul_hi_u32 v2, v1, v2
	v_add_u32_e32 v1, v1, v2
	s_waitcnt vmcnt(0)
	v_mul_hi_u32 v1, v0, v1
	v_mul_lo_u32 v2, v1, s90
	v_sub_u32_e32 v2, v0, v2
	v_add_u32_e32 v3, 1, v1
	v_cmp_le_u32_e32 vcc, s90, v2
	v_add_u32_e32 v0, 1, v0
	s_nop 0
	v_cndmask_b32_e32 v1, v1, v3, vcc
	v_subrev_u32_e32 v3, s90, v2
	v_cndmask_b32_e32 v2, v2, v3, vcc
	v_add_u32_e32 v3, 1, v1
	v_cmp_le_u32_e32 vcc, s90, v2
	s_nop 1
	v_cndmask_b32_e32 v2, v1, v3, vcc
	v_mul_lo_u32 v1, s90, v2
	v_add_u32_e32 v1, s90, v1
	v_cmp_ne_u32_e32 vcc, v0, v1
	s_and_saveexec_b64 s[6:7], vcc
	s_xor_b64 s[6:7], exec, s[6:7]
	s_cbranch_execz .LBB0_478
	v_mov_b32_e32 v0, 0xe7a3500
	v_mov_b32_e32 v1, s61
	v_add_co_u32_e32 v0, vcc, s60, v0
	s_nop 1
	v_addc_co_u32_e32 v1, vcc, 0, v1, vcc
	global_load_dword v0, v[0:1], off sc1
	s_waitcnt vmcnt(0)
	v_cmp_eq_u32_e32 vcc, v0, v2
	s_and_saveexec_b64 s[8:9], vcc
	s_cbranch_execz .LBB0_477
	s_add_u32 s10, s60, 0xe7a3500
	s_addc_u32 s11, s61, 0
	v_mov_b32_e32 v0, s10
	v_mov_b32_e32 v1, s11
	s_nop 0
	s_add_u32 s10, s60, 0xe7a0200
	s_addc_u32 s11, s61, 0
	s_mov_b32 s3, 1
	s_mov_b64 s[16:17], 0
	v_mov_b32_e32 v3, 0
	s_branch .LBB0_468

; __device__ __forceinline__ unsigned xb_ld(unsigned* p) { return __hip_atomic_load(p, __ATOMIC_RELAXED, __HIP_MEMORY_SCOPE_AGENT); }
; __device__ __forceinline__ unsigned xb_add(unsigned* p, unsigned v) { return __hip_atomic_fetch_add(p, v, __ATOMIC_RELAXED, __HIP_MEMORY_SCOPE_AGENT); }
; #define XB_SPIN(cond, bar) do { unsigned _sp = 0; while (cond) { __builtin_amdgcn_s_sleep(1); \
;     if ((++_sp & 255u) == 0u) { if (xb_ld(&(bar)[XB_TMO])) break; if (_sp > XB_SPIN_CAP) { atomicAdd(&(bar)[XB_TMO], 1u); break; } } } } while (0)
; __device__ __forceinline__ void xcd_barrier(const XcdBarrier& b) {
;     ...
;   if (threadIdx.x == 0) {
;     unsigned* bar = b.bar;
;     __builtin_amdgcn_s_waitcnt(0);
;     const unsigned old = xb_add(&bar[XB_XSUB(b.x)], 1u);
;     const unsigned gen = old / b.nloc;
;     if (old + 1u == (gen + 1u) * b.nloc) {
;       __builtin_amdgcn_fence(__ATOMIC_RELEASE, "agent");
;       asm volatile("s_waitcnt vmcnt(0)" ::: "memory");
;       const unsigned og = xb_add(&bar[XB_TOP], 1u);
;       const unsigned tg = og / b.nx;
;       if (og + 1u == (tg + 1u) * b.nx) xb_add(&bar[XB_TOPGEN], 1u);
;       else XB_SPIN(xb_ld(&bar[XB_TOPGEN]) == tg, bar);
;       __builtin_amdgcn_fence(__ATOMIC_ACQUIRE, "agent");
;       xb_add(&bar[XB_XGEN(b.x)], 1u);
;     } else {
;       XB_SPIN(xb_ld(&bar[XB_XGEN(b.x)]) == gen, bar);
;       __builtin_amdgcn_fence(__ATOMIC_ACQUIRE, "agent");
;     }
.LBB0_499:
	s_or_b64 exec, exec, s[4:5]
	s_waitcnt vmcnt(0)
	s_barrier
	s_and_saveexec_b64 s[2:3], s[0:1]
	s_cbranch_execz .LBB0_532
	v_add_co_u32_e32 v0, vcc, 0x1000, v192
	v_mov_b32_e32 v2, 1
	s_nop 0
	v_addc_co_u32_e32 v1, vcc, 0, v193, vcc
	s_waitcnt vmcnt(0) expcnt(0) lgkmcnt(0)
	global_atomic_add v0, v[0:1], v2, off offset:1024 sc0
	v_mul_f32_e32 v1, 0x4f7ffffe, v207
	v_cvt_u32_f32_e32 v1, v1
	s_sub_i32 s4, 0, s90
	v_mul_lo_u32 v2, s4, v1
	v_mul_hi_u32 v2, v1, v2
	v_add_u32_e32 v1, v1, v2
	s_waitcnt vmcnt(0)
	v_mul_hi_u32 v1, v0, v1
	v_mul_lo_u32 v2, v1, s90
	v_sub_u32_e32 v2, v0, v2
	v_add_u32_e32 v3, 1, v1
	v_cmp_le_u32_e32 vcc, s90, v2
	v_add_u32_e32 v0, 1, v0
	s_nop 0
	v_cndmask_b32_e32 v1, v1, v3, vcc
	v_subrev_u32_e32 v3, s90, v2
	v_cndmask_b32_e32 v2, v2, v3, vcc
	v_add_u32_e32 v3, 1, v1
	v_cmp_le_u32_e32 vcc, s90, v2
	s_nop 1
	v_cndmask_b32_e32 v2, v1, v3, vcc
	v_mul_lo_u32 v1, s90, v2
	v_add_u32_e32 v1, s90, v1
	v_cmp_ne_u32_e32 vcc, v0, v1
	s_and_saveexec_b64 s[4:5], vcc
	s_xor_b64 s[4:5], exec, s[4:5]
	s_cbranch_execz .LBB0_514
	v_mov_b32_e32 v0, 0xe7a3500
	v_mov_b32_e32 v1, s61
	v_add_co_u32_e32 v0, vcc, s60, v0
	s_nop 1
	v_addc_co_u32_e32 v1, vcc, 0, v1, vcc
	global_load_dword v0, v[0:1], off sc1
	s_waitcnt vmcnt(0)
	v_cmp_eq_u32_e32 vcc, v0, v2
	s_and_saveexec_b64 s[6:7], vcc
	s_cbranch_execz .LBB0_513
	s_add_u32 s8, s60, 0xe7a3500
	s_addc_u32 s9, s61, 0
	v_mov_b32_e32 v0, s8
	v_mov_b32_e32 v1, s9
	s_nop 0
	s_add_u32 s8, s60, 0xe7a0200
	s_addc_u32 s9, s61, 0
	s_mov_b32 s19, 1
	s_mov_b64 s[10:11], 0
	v_mov_b32_e32 v3, 0
	s_branch .LBB0_504

; __device__ __forceinline__ unsigned xb_ld(unsigned* p) { return __hip_atomic_load(p, __ATOMIC_RELAXED, __HIP_MEMORY_SCOPE_AGENT); }
; __device__ __forceinline__ unsigned xb_add(unsigned* p, unsigned v) { return __hip_atomic_fetch_add(p, v, __ATOMIC_RELAXED, __HIP_MEMORY_SCOPE_AGENT); }
; #define XB_SPIN(cond, bar) do { unsigned _sp = 0; while (cond) { __builtin_amdgcn_s_sleep(1); \
;     if ((++_sp & 255u) == 0u) { if (xb_ld(&(bar)[XB_TMO])) break; if (_sp > XB_SPIN_CAP) { atomicAdd(&(bar)[XB_TMO], 1u); break; } } } } while (0)
; __device__ __forceinline__ void xcd_barrier(const XcdBarrier& b) {
;     ...
;   if (threadIdx.x == 0) {
;     unsigned* bar = b.bar;
;     __builtin_amdgcn_s_waitcnt(0);
;     const unsigned old = xb_add(&bar[XB_XSUB(b.x)], 1u);
;     const unsigned gen = old / b.nloc;
;     if (old + 1u == (gen + 1u) * b.nloc) {
;       __builtin_amdgcn_fence(__ATOMIC_RELEASE, "agent");
;       asm volatile("s_waitcnt vmcnt(0)" ::: "memory");
;       const unsigned og = xb_add(&bar[XB_TOP], 1u);
;       const unsigned tg = og / b.nx;
;       if (og + 1u == (tg + 1u) * b.nx) xb_add(&bar[XB_TOPGEN], 1u);
;       else XB_SPIN(xb_ld(&bar[XB_TOPGEN]) == tg, bar);
;       __builtin_amdgcn_fence(__ATOMIC_ACQUIRE, "agent");
;       xb_add(&bar[XB_XGEN(b.x)], 1u);
;     } else {
;       XB_SPIN(xb_ld(&bar[XB_XGEN(b.x)]) == gen, bar);
;       __builtin_amdgcn_fence(__ATOMIC_ACQUIRE, "agent");
;     }
.LBB0_542:
	s_waitcnt vmcnt(0)
	s_barrier
	s_and_saveexec_b64 s[2:3], s[0:1]
	s_cbranch_execz .LBB0_575
	s_waitcnt vmcnt(1)
	v_add_co_u32_e32 v0, vcc, 0x1000, v192
	v_mov_b32_e32 v2, 1
	s_nop 0
	v_addc_co_u32_e32 v1, vcc, 0, v193, vcc
	s_waitcnt vmcnt(0) expcnt(0) lgkmcnt(0)
	global_atomic_add v0, v[0:1], v2, off offset:1024 sc0
	v_mul_f32_e32 v1, 0x4f7ffffe, v207
	v_cvt_u32_f32_e32 v1, v1
	s_sub_i32 s4, 0, s90
	v_mul_lo_u32 v2, s4, v1
	v_mul_hi_u32 v2, v1, v2
	v_add_u32_e32 v1, v1, v2
	s_waitcnt vmcnt(0)
	v_mul_hi_u32 v1, v0, v1
	v_mul_lo_u32 v2, v1, s90
	v_sub_u32_e32 v2, v0, v2
	v_add_u32_e32 v3, 1, v1
	v_cmp_le_u32_e32 vcc, s90, v2
	v_add_u32_e32 v0, 1, v0
	s_nop 0
	v_cndmask_b32_e32 v1, v1, v3, vcc
	v_subrev_u32_e32 v3, s90, v2
	v_cndmask_b32_e32 v2, v2, v3, vcc
	v_add_u32_e32 v3, 1, v1
	v_cmp_le_u32_e32 vcc, s90, v2
	s_nop 1
	v_cndmask_b32_e32 v2, v1, v3, vcc
	v_mul_lo_u32 v1, s90, v2
	v_add_u32_e32 v1, s90, v1
	v_cmp_ne_u32_e32 vcc, v0, v1
	s_and_saveexec_b64 s[4:5], vcc
	s_xor_b64 s[4:5], exec, s[4:5]
	s_cbranch_execz .LBB0_557
	v_mov_b32_e32 v0, 0xe7a3500
	v_mov_b32_e32 v1, s61
	v_add_co_u32_e32 v0, vcc, s60, v0
	s_nop 1
	v_addc_co_u32_e32 v1, vcc, 0, v1, vcc
	global_load_dword v0, v[0:1], off sc1
	s_waitcnt vmcnt(0)
	v_cmp_eq_u32_e32 vcc, v0, v2
	s_and_saveexec_b64 s[6:7], vcc
	s_cbranch_execz .LBB0_556
	s_add_u32 s8, s60, 0xe7a3500
	s_addc_u32 s9, s61, 0
	v_mov_b32_e32 v0, s8
	v_mov_b32_e32 v1, s9
	s_nop 0
	s_add_u32 s8, s60, 0xe7a0200
	s_addc_u32 s9, s61, 0
	s_mov_b32 s19, 1
	s_mov_b64 s[10:11], 0
	v_mov_b32_e32 v3, 0
	s_branch .LBB0_547

; __device__ __forceinline__ unsigned xb_ld(unsigned* p) { return __hip_atomic_load(p, __ATOMIC_RELAXED, __HIP_MEMORY_SCOPE_AGENT); }
; __device__ __forceinline__ unsigned xb_add(unsigned* p, unsigned v) { return __hip_atomic_fetch_add(p, v, __ATOMIC_RELAXED, __HIP_MEMORY_SCOPE_AGENT); }
; #define XB_SPIN(cond, bar) do { unsigned _sp = 0; while (cond) { __builtin_amdgcn_s_sleep(1); \
;     if ((++_sp & 255u) == 0u) { if (xb_ld(&(bar)[XB_TMO])) break; if (_sp > XB_SPIN_CAP) { atomicAdd(&(bar)[XB_TMO], 1u); break; } } } } while (0)
; __device__ __forceinline__ void xcd_barrier(const XcdBarrier& b) {
;     ...
;   if (threadIdx.x == 0) {
;     unsigned* bar = b.bar;
;     __builtin_amdgcn_s_waitcnt(0);
;     const unsigned old = xb_add(&bar[XB_XSUB(b.x)], 1u);
;     const unsigned gen = old / b.nloc;
;     if (old + 1u == (gen + 1u) * b.nloc) {
;       __builtin_amdgcn_fence(__ATOMIC_RELEASE, "agent");
;       asm volatile("s_waitcnt vmcnt(0)" ::: "memory");
;       const unsigned og = xb_add(&bar[XB_TOP], 1u);
;       const unsigned tg = og / b.nx;
;       if (og + 1u == (tg + 1u) * b.nx) xb_add(&bar[XB_TOPGEN], 1u);
;       else XB_SPIN(xb_ld(&bar[XB_TOPGEN]) == tg, bar);
;       __builtin_amdgcn_fence(__ATOMIC_ACQUIRE, "agent");
;       xb_add(&bar[XB_XGEN(b.x)], 1u);
;     } else {
;       XB_SPIN(xb_ld(&bar[XB_XGEN(b.x)]) == gen, bar);
;       __builtin_amdgcn_fence(__ATOMIC_ACQUIRE, "agent");
;     }
.LBB0_586:
	s_or_b64 exec, exec, s[2:3]
	s_waitcnt vmcnt(0)
	s_barrier
	s_and_saveexec_b64 s[2:3], s[0:1]
	s_cbranch_execz .LBB0_619
	v_add_co_u32_e32 v0, vcc, 0x1000, v192
	v_mov_b32_e32 v2, 1
	s_nop 0
	v_addc_co_u32_e32 v1, vcc, 0, v193, vcc
	s_waitcnt vmcnt(0) expcnt(0) lgkmcnt(0)
	global_atomic_add v0, v[0:1], v2, off offset:1024 sc0
	v_mul_f32_e32 v1, 0x4f7ffffe, v207
	v_cvt_u32_f32_e32 v1, v1
	s_sub_i32 s4, 0, s90
	v_mul_lo_u32 v2, s4, v1
	v_mul_hi_u32 v2, v1, v2
	v_add_u32_e32 v1, v1, v2
	s_waitcnt vmcnt(0)
	v_mul_hi_u32 v1, v0, v1
	v_mul_lo_u32 v2, v1, s90
	v_sub_u32_e32 v2, v0, v2
	v_add_u32_e32 v3, 1, v1
	v_cmp_le_u32_e32 vcc, s90, v2
	v_add_u32_e32 v0, 1, v0
	s_nop 0
	v_cndmask_b32_e32 v1, v1, v3, vcc
	v_subrev_u32_e32 v3, s90, v2
	v_cndmask_b32_e32 v2, v2, v3, vcc
	v_add_u32_e32 v3, 1, v1
	v_cmp_le_u32_e32 vcc, s90, v2
	s_nop 1
	v_cndmask_b32_e32 v2, v1, v3, vcc
	v_mul_lo_u32 v1, s90, v2
	v_add_u32_e32 v1, s90, v1
	v_cmp_ne_u32_e32 vcc, v0, v1
	s_and_saveexec_b64 s[4:5], vcc
	s_xor_b64 s[4:5], exec, s[4:5]
	s_cbranch_execz .LBB0_601
	v_mov_b32_e32 v0, 0xe7a3500
	v_mov_b32_e32 v1, s61
	v_add_co_u32_e32 v0, vcc, s60, v0
	s_nop 1
	v_addc_co_u32_e32 v1, vcc, 0, v1, vcc
	global_load_dword v0, v[0:1], off sc1
	s_waitcnt vmcnt(0)
	v_cmp_eq_u32_e32 vcc, v0, v2
	s_and_saveexec_b64 s[6:7], vcc
	s_cbranch_execz .LBB0_600
	s_add_u32 s8, s60, 0xe7a3500
	s_addc_u32 s9, s61, 0
	v_mov_b32_e32 v0, s8
	v_mov_b32_e32 v1, s9
	s_nop 0
	s_add_u32 s8, s60, 0xe7a0200
	s_addc_u32 s9, s61, 0
	s_mov_b32 s19, 1
	s_mov_b64 s[16:17], 0
	v_mov_b32_e32 v3, 0
	s_branch .LBB0_591

; __device__ __forceinline__ unsigned xb_ld(unsigned* p) { return __hip_atomic_load(p, __ATOMIC_RELAXED, __HIP_MEMORY_SCOPE_AGENT); }
; __device__ __forceinline__ unsigned xb_add(unsigned* p, unsigned v) { return __hip_atomic_fetch_add(p, v, __ATOMIC_RELAXED, __HIP_MEMORY_SCOPE_AGENT); }
; #define XB_SPIN(cond, bar) do { unsigned _sp = 0; while (cond) { __builtin_amdgcn_s_sleep(1); \
;     if ((++_sp & 255u) == 0u) { if (xb_ld(&(bar)[XB_TMO])) break; if (_sp > XB_SPIN_CAP) { atomicAdd(&(bar)[XB_TMO], 1u); break; } } } } while (0)
; __device__ __forceinline__ void xcd_barrier(const XcdBarrier& b) {
;     ...
;   if (threadIdx.x == 0) {
;     unsigned* bar = b.bar;
;     __builtin_amdgcn_s_waitcnt(0);
;     const unsigned old = xb_add(&bar[XB_XSUB(b.x)], 1u);
;     const unsigned gen = old / b.nloc;
;     if (old + 1u == (gen + 1u) * b.nloc) {
;       __builtin_amdgcn_fence(__ATOMIC_RELEASE, "agent");
;       asm volatile("s_waitcnt vmcnt(0)" ::: "memory");
;       const unsigned og = xb_add(&bar[XB_TOP], 1u);
;       const unsigned tg = og / b.nx;
;       if (og + 1u == (tg + 1u) * b.nx) xb_add(&bar[XB_TOPGEN], 1u);
;       else XB_SPIN(xb_ld(&bar[XB_TOPGEN]) == tg, bar);
;       __builtin_amdgcn_fence(__ATOMIC_ACQUIRE, "agent");
;       xb_add(&bar[XB_XGEN(b.x)], 1u);
;     } else {
;       XB_SPIN(xb_ld(&bar[XB_XGEN(b.x)]) == gen, bar);
;       __builtin_amdgcn_fence(__ATOMIC_ACQUIRE, "agent");
;     }
.LBB0_624:
	s_waitcnt vmcnt(0)
	s_barrier
	s_and_saveexec_b64 s[2:3], s[0:1]
	s_cbranch_execz .LBB0_657
	s_waitcnt vmcnt(8)
	v_add_co_u32_e32 v0, vcc, 0x1000, v192
	v_mov_b32_e32 v2, 1
	s_nop 0
	v_addc_co_u32_e32 v1, vcc, 0, v193, vcc
	s_waitcnt vmcnt(0) expcnt(0) lgkmcnt(0)
	global_atomic_add v0, v[0:1], v2, off offset:1024 sc0
	v_mul_f32_e32 v1, 0x4f7ffffe, v207
	v_cvt_u32_f32_e32 v1, v1
	s_sub_i32 s0, 0, s90
	v_mul_lo_u32 v2, s0, v1
	v_mul_hi_u32 v2, v1, v2
	v_add_u32_e32 v1, v1, v2
	s_waitcnt vmcnt(0)
	v_mul_hi_u32 v1, v0, v1
	v_mul_lo_u32 v2, v1, s90
	v_sub_u32_e32 v2, v0, v2
	v_add_u32_e32 v3, 1, v1
	v_cmp_le_u32_e32 vcc, s90, v2
	v_add_u32_e32 v0, 1, v0
	s_nop 0
	v_cndmask_b32_e32 v1, v1, v3, vcc
	v_subrev_u32_e32 v3, s90, v2
	v_cndmask_b32_e32 v2, v2, v3, vcc
	v_add_u32_e32 v3, 1, v1
	v_cmp_le_u32_e32 vcc, s90, v2
	s_nop 1
	v_cndmask_b32_e32 v2, v1, v3, vcc
	v_mul_lo_u32 v1, s90, v2
	v_add_u32_e32 v1, s90, v1
	v_cmp_ne_u32_e32 vcc, v0, v1
	s_and_saveexec_b64 s[0:1], vcc
	s_xor_b64 s[0:1], exec, s[0:1]
	s_cbranch_execz .LBB0_639
	v_mov_b32_e32 v0, 0xe7a3500
	v_mov_b32_e32 v1, s61
	v_add_co_u32_e32 v0, vcc, s60, v0
	s_nop 1
	v_addc_co_u32_e32 v1, vcc, 0, v1, vcc
	global_load_dword v0, v[0:1], off sc1
	s_waitcnt vmcnt(0)
	v_cmp_eq_u32_e32 vcc, v0, v2
	s_and_saveexec_b64 s[4:5], vcc
	s_cbranch_execz .LBB0_638
	s_add_u32 s6, s60, 0xe7a3500
	s_addc_u32 s7, s61, 0
	v_mov_b32_e32 v0, s6
	v_mov_b32_e32 v1, s7
	s_nop 0
	s_add_u32 s6, s60, 0xe7a0200
	s_addc_u32 s7, s61, 0
	s_mov_b32 s22, 1
	s_mov_b64 s[8:9], 0
	v_mov_b32_e32 v3, 0
	s_branch .LBB0_629
